# one static s_setprio 1 for waves 0-3 during the attention prompt units (other half than the previous version)
# speedup vs baseline: 1.0604x; 1.0010x over previous
; __device__ __forceinline__ void fox_attention(const Args& a, LAS unsigned char* lds, int vcu, int G) {
;     ...
;             if (G == 256) {
;                 const int bh = vcu >> 1, s0 = 2 * (vcu & 1);
; #pragma unroll 1
;                 for (int i = 0; i < 4; ++i) attn_unit_prompt(a, lds, bh >> 4, bh & 15, (i & 1) ? s0 + (i >> 1) : 7 - s0 - (i >> 1));
.LBB0_1716:
	s_setprio 0
	v_readfirstlane_b32 s98, v0
	s_nop 3
	s_lshr_b32 s98, s98, 6
	s_cmp_ge_u32 s98, 4
	s_cbranch_scc1 .Lp10_prio_done
	s_setprio 1
